# residual GEMM loop: same SGPR-base LDS-DMA addressing (no per-DMA 64-bit VALU add)
# baseline (speedup 1.0000x reference)
; #define PG8_STAGE(bufoff, gbase, voff) do { _Pragma("unroll") for (int _i = 0; _i < 2; ++_i) \
;         __builtin_amdgcn_global_load_lds((const unsigned*)((const char*)(gbase) + (voff)[_i]), (LAS unsigned*)(lds + (bufoff) + ldsw + _i * 8192), 16, 0, 0); } while (0)
; #define PG8_LDA(dst, b, h) do { _Pragma("unroll") for (int m = 0; m < 4; ++m) _Pragma("unroll") for (int k = 0; k < 2; ++k) dst[m][k] = *(const LAS bf16x8*)(lds + PG8_SA(b, h) + aoff + m * 2048 + k * 1024); } while (0)
; #define PG8_LDB(dst, b, h) do { _Pragma("unroll") for (int n = 0; n < 2; ++n) _Pragma("unroll") for (int k = 0; k < 2; ++k) dst[n][k] = *(const LAS bf16x8*)(lds + PG8_SB(b, h) + boff + n * 2048 + k * 1024); } while (0)
; #define PG8_MMA(ai, bj, At, Bt) do { __builtin_amdgcn_s_setprio(1); _Pragma("unroll") for (int m = 0; m < 4; ++m) _Pragma("unroll") for (int n = 0; n < 2; ++n) _Pragma("unroll") for (int k = 0; k < 2; ++k) \
;         acc[ai][bj][m][n] = __builtin_amdgcn_mfma_f32_16x16x32_bf16(Bt[n][k], At[m][k], acc[ai][bj][m][n], 0, 0, 0); __builtin_amdgcn_s_setprio(0); } while (0)
; #define PG8_WAIT_V(n) asm volatile("s_waitcnt vmcnt(" #n ")" ::: "memory")
; #define PG8_WAIT_L(n) asm volatile("s_waitcnt lgkmcnt(" #n ")" ::: "memory")
; #define PG8_BAR __builtin_amdgcn_s_barrier()
; #define PG8_SCHED __builtin_amdgcn_sched_barrier(0)
; template <class Epi>
; DI void gemm_phase(LAS unsigned char* lds, const Gemm g, const StaticOrder S, const Epi E) {
;     ...
;             const bool last = (t == nt - 2);
;             const char* a1 = cA + (size_t)(t + 1) * kstep;
;             const char* a2 = last ? nA : cA + (size_t)(t + 2) * kstep; const char* b2 = last ? nB : cB + (size_t)(t + 2) * kstep;
;             const char* a3 = a2 + kstep; const char* b3 = b2 + kstep;
;             PG8_LDB(B0, 0, 0); PG8_LDB(B1, 0, 1); PG8_SCHED; PG8_LDA(At, 0, 0); PG8_STAGE(PG8_SA(1, 1), a1 + hstepA, voffA);
;             PG8_WAIT_V(8); PG8_WAIT_L(0); PG8_BAR; PG8_MMA(0, 0, At, B0); PG8_MMA(0, 1, At, B1); PG8_BAR; PG8_SCHED;
;             PG8_LDA(At, 0, 1); PG8_STAGE(PG8_SB(0, 0), b2, voffB); PG8_STAGE(PG8_SB(0, 1), b2 + hstepB, voffB); PG8_STAGE(PG8_SA(0, 0), a2, voffA);
.LBB0_430:
	s_add_i32 vcc_lo, s30, 2
	s_add_u32 s20, s42, 0x80
	s_addc_u32 s21, s43, 0
	s_add_i32 vcc_hi, 0, 0x10000
	s_cmp_eq_u32 s65, s30
	s_cselect_b32 s31, s67, s21
	s_cselect_b32 s30, s66, s20
	s_cselect_b32 s21, s69, s45
	s_cselect_b32 s20, s68, s44
	s_add_u32 s98, s20, 0x80
	s_addc_u32 s99, s21, 0
	s_add_u32 s100, s98, s77
	s_addc_u32 s101, s99, 0
	s_add_i32 s26, 0, 0x14000
	v_add_u32_e32 v162, vcc_hi, v175
	v_add_u32_e32 v177, s26, v175
	ds_read_b128 v[128:131], v162
	ds_read_b128 v[142:145], v162 offset:1024
	ds_read_b128 v[158:161], v162 offset:2048
	ds_read_b128 v[162:165], v162 offset:3072
	ds_read_b128 v[166:169], v177
	ds_read_b128 v[170:173], v177 offset:1024
	ds_read_b128 v[178:181], v177 offset:2048
	ds_read_b128 v[182:185], v177 offset:3072
	s_add_i32 m0, s51, 0xc000
	ds_read_b128 v[186:189], v176
	ds_read_b128 v[190:193], v176 offset:1024
	ds_read_b128 v[194:197], v176 offset:2048
	ds_read_b128 v[220:223], v176 offset:3072
	ds_read_b128 v[230:233], v176 offset:4096
	ds_read_b128 v[234:237], v176 offset:5120
	ds_read_b128 v[238:241], v176 offset:6144
	ds_read_b128 v[242:245], v176 offset:7168
	global_load_lds_dwordx4 v138, s[42:43]
	s_add_i32 m0, s51, 0xe000
	s_nop 0
	global_load_lds_dwordx4 v140, s[42:43]
	s_waitcnt vmcnt(8)
	s_waitcnt lgkmcnt(0)
	s_barrier
	s_setprio 1
	s_waitcnt lgkmcnt(0)
	v_mfma_f32_16x16x32_bf16 v[124:127], v[128:131], v[186:189], v[124:127]
	v_mfma_f32_16x16x32_bf16 v[120:123], v[158:161], v[186:189], v[120:123]
	v_mfma_f32_16x16x32_bf16 v[116:119], v[128:131], v[194:197], v[116:119]
	v_mfma_f32_16x16x32_bf16 v[112:115], v[158:161], v[194:197], v[112:115]
	v_mfma_f32_16x16x32_bf16 v[108:111], v[128:131], v[230:233], v[108:111]
	v_mfma_f32_16x16x32_bf16 v[104:107], v[158:161], v[230:233], v[104:107]
	v_mfma_f32_16x16x32_bf16 v[100:103], v[128:131], v[238:241], v[100:103]
	v_mfma_f32_16x16x32_bf16 v[96:99], v[158:161], v[238:241], v[96:99]
	v_mfma_f32_16x16x32_bf16 v[124:127], v[142:145], v[190:193], v[124:127]
	v_mfma_f32_16x16x32_bf16 v[120:123], v[162:165], v[190:193], v[120:123]
	v_mfma_f32_16x16x32_bf16 v[116:119], v[142:145], v[220:223], v[116:119]
	v_mfma_f32_16x16x32_bf16 v[112:115], v[162:165], v[220:223], v[112:115]
	v_mfma_f32_16x16x32_bf16 v[108:111], v[142:145], v[234:237], v[108:111]
	v_mfma_f32_16x16x32_bf16 v[104:107], v[162:165], v[234:237], v[104:107]
	v_mfma_f32_16x16x32_bf16 v[100:103], v[142:145], v[242:245], v[100:103]
	v_mfma_f32_16x16x32_bf16 v[96:99], v[162:165], v[242:245], v[96:99]
	s_setprio 0
	s_setprio 1
	v_mfma_f32_16x16x32_bf16 v[60:63], v[166:169], v[186:189], v[60:63]
	v_mfma_f32_16x16x32_bf16 v[56:59], v[178:181], v[186:189], v[56:59]
	v_mfma_f32_16x16x32_bf16 v[52:55], v[166:169], v[194:197], v[52:55]
	v_mfma_f32_16x16x32_bf16 v[48:51], v[178:181], v[194:197], v[48:51]
	v_mfma_f32_16x16x32_bf16 v[44:47], v[166:169], v[230:233], v[44:47]
	v_mfma_f32_16x16x32_bf16 v[40:43], v[178:181], v[230:233], v[40:43]
	v_mfma_f32_16x16x32_bf16 v[36:39], v[166:169], v[238:241], v[36:39]
	v_mfma_f32_16x16x32_bf16 v[32:35], v[178:181], v[238:241], v[32:35]
	v_mfma_f32_16x16x32_bf16 v[60:63], v[170:173], v[190:193], v[60:63]
	v_mfma_f32_16x16x32_bf16 v[56:59], v[182:185], v[190:193], v[56:59]
	v_mfma_f32_16x16x32_bf16 v[52:55], v[170:173], v[220:223], v[52:55]
	v_mfma_f32_16x16x32_bf16 v[48:51], v[182:185], v[220:223], v[48:51]
	v_mfma_f32_16x16x32_bf16 v[44:47], v[170:173], v[234:237], v[44:47]
	v_mfma_f32_16x16x32_bf16 v[40:43], v[182:185], v[234:237], v[40:43]
	v_mfma_f32_16x16x32_bf16 v[36:39], v[170:173], v[242:245], v[36:39]
	v_mfma_f32_16x16x32_bf16 v[32:35], v[182:185], v[242:245], v[32:35]
	s_setprio 0
	s_barrier
	s_add_i32 s27, vcc_hi, s81
	s_mov_b32 m0, s27
	ds_read_b128 v[186:189], v176 offset:16384
	ds_read_b128 v[190:193], v176 offset:17408
	ds_read_b128 v[194:197], v176 offset:18432
	ds_read_b128 v[220:223], v176 offset:19456
	ds_read_b128 v[230:233], v176 offset:20480
	ds_read_b128 v[234:237], v176 offset:21504
	ds_read_b128 v[238:241], v176 offset:22528
	ds_read_b128 v[242:245], v176 offset:23552
	global_load_lds_dwordx4 v146, s[20:21]
	s_add_i32 m0, s27, 0x2000
	s_add_i32 s26, s26, s81
	global_load_lds_dwordx4 v136, s[20:21]
	s_add_u32 s20, s20, s77
	s_addc_u32 s21, s21, 0
	s_mov_b32 m0, s26
	s_nop 0
	global_load_lds_dwordx4 v146, s[20:21]
	s_add_i32 m0, s26, 0x2000
	s_nop 0
	global_load_lds_dwordx4 v136, s[20:21]
	s_mov_b32 m0, s51
	s_nop 0
	global_load_lds_dwordx4 v132, s[30:31]
	s_mov_b32 m0, s70
	s_nop 0
	global_load_lds_dwordx4 v134, s[30:31]
	s_waitcnt vmcnt(8)
	s_waitcnt lgkmcnt(0)
	s_barrier
; #define PG8_STAGE(bufoff, gbase, voff) do { _Pragma("unroll") for (int _i = 0; _i < 2; ++_i) \
;         __builtin_amdgcn_global_load_lds((const unsigned*)((const char*)(gbase) + (voff)[_i]), (LAS unsigned*)(lds + (bufoff) + ldsw + _i * 8192), 16, 0, 0); } while (0)
; #define PG8_LDA(dst, b, h) do { _Pragma("unroll") for (int m = 0; m < 4; ++m) _Pragma("unroll") for (int k = 0; k < 2; ++k) dst[m][k] = *(const LAS bf16x8*)(lds + PG8_SA(b, h) + aoff + m * 2048 + k * 1024); } while (0)
; #define PG8_LDB(dst, b, h) do { _Pragma("unroll") for (int n = 0; n < 2; ++n) _Pragma("unroll") for (int k = 0; k < 2; ++k) dst[n][k] = *(const LAS bf16x8*)(lds + PG8_SB(b, h) + boff + n * 2048 + k * 1024); } while (0)
; #define PG8_MMA(ai, bj, At, Bt) do { __builtin_amdgcn_s_setprio(1); _Pragma("unroll") for (int m = 0; m < 4; ++m) _Pragma("unroll") for (int n = 0; n < 2; ++n) _Pragma("unroll") for (int k = 0; k < 2; ++k) \
;         acc[ai][bj][m][n] = __builtin_amdgcn_mfma_f32_16x16x32_bf16(Bt[n][k], At[m][k], acc[ai][bj][m][n], 0, 0, 0); __builtin_amdgcn_s_setprio(0); } while (0)
; #define PG8_WAIT_V(n) asm volatile("s_waitcnt vmcnt(" #n ")" ::: "memory")
; #define PG8_WAIT_L(n) asm volatile("s_waitcnt lgkmcnt(" #n ")" ::: "memory")
; #define PG8_BAR __builtin_amdgcn_s_barrier()
; #define PG8_SCHED __builtin_amdgcn_sched_barrier(0)
; template <class Epi>
; DI void gemm_phase(LAS unsigned char* lds, const Gemm g, const StaticOrder S, const Epi E) {
;     ...
;             PG8_WAIT_V(8); PG8_WAIT_L(0); PG8_BAR; PG8_MMA(1, 0, At, B0); PG8_MMA(1, 1, At, B1); PG8_BAR; PG8_SCHED;
;             PG8_LDB(B0, 1, 0); PG8_LDB(B1, 1, 1); PG8_SCHED; PG8_LDA(At, 1, 0); PG8_STAGE(PG8_SA(0, 1), a2 + hstepA, voffA);
;             PG8_WAIT_V(8); PG8_WAIT_L(0); PG8_BAR; PG8_MMA(0, 0, At, B0); PG8_MMA(0, 1, At, B1); PG8_BAR; PG8_SCHED;
	s_setprio 1
	s_waitcnt lgkmcnt(0)
	v_mfma_f32_16x16x32_bf16 v[92:95], v[128:131], v[186:189], v[92:95]
	v_mfma_f32_16x16x32_bf16 v[88:91], v[158:161], v[186:189], v[88:91]
	v_mfma_f32_16x16x32_bf16 v[84:87], v[128:131], v[194:197], v[84:87]
	v_mfma_f32_16x16x32_bf16 v[80:83], v[158:161], v[194:197], v[80:83]
	v_mfma_f32_16x16x32_bf16 v[76:79], v[128:131], v[230:233], v[76:79]
	v_mfma_f32_16x16x32_bf16 v[72:75], v[158:161], v[230:233], v[72:75]
	v_mfma_f32_16x16x32_bf16 v[68:71], v[128:131], v[238:241], v[68:71]
	v_mfma_f32_16x16x32_bf16 v[64:67], v[158:161], v[238:241], v[64:67]
	v_mfma_f32_16x16x32_bf16 v[92:95], v[142:145], v[190:193], v[92:95]
	v_mfma_f32_16x16x32_bf16 v[88:91], v[162:165], v[190:193], v[88:91]
	v_mfma_f32_16x16x32_bf16 v[84:87], v[142:145], v[220:223], v[84:87]
	v_mfma_f32_16x16x32_bf16 v[80:83], v[162:165], v[220:223], v[80:83]
	v_mfma_f32_16x16x32_bf16 v[76:79], v[142:145], v[234:237], v[76:79]
	v_mfma_f32_16x16x32_bf16 v[72:75], v[162:165], v[234:237], v[72:75]
	v_mfma_f32_16x16x32_bf16 v[68:71], v[142:145], v[242:245], v[68:71]
	v_mfma_f32_16x16x32_bf16 v[64:67], v[162:165], v[242:245], v[64:67]
	s_setprio 0
	s_setprio 1
	v_mfma_f32_16x16x32_bf16 v[28:31], v[166:169], v[186:189], v[28:31]
	v_mfma_f32_16x16x32_bf16 v[24:27], v[178:181], v[186:189], v[24:27]
	v_mfma_f32_16x16x32_bf16 v[20:23], v[166:169], v[194:197], v[20:23]
	v_mfma_f32_16x16x32_bf16 v[16:19], v[178:181], v[194:197], v[16:19]
	v_mfma_f32_16x16x32_bf16 v[12:15], v[166:169], v[230:233], v[12:15]
	v_mfma_f32_16x16x32_bf16 v[8:11], v[178:181], v[230:233], v[8:11]
	v_mfma_f32_16x16x32_bf16 v[4:7], v[166:169], v[238:241], v[4:7]
	v_mfma_f32_16x16x32_bf16 v[0:3], v[178:181], v[238:241], v[0:3]
	v_mfma_f32_16x16x32_bf16 v[28:31], v[170:173], v[190:193], v[28:31]
	v_mfma_f32_16x16x32_bf16 v[24:27], v[182:185], v[190:193], v[24:27]
	v_mfma_f32_16x16x32_bf16 v[20:23], v[170:173], v[220:223], v[20:23]
	v_mfma_f32_16x16x32_bf16 v[16:19], v[182:185], v[220:223], v[16:19]
	v_mfma_f32_16x16x32_bf16 v[12:15], v[170:173], v[234:237], v[12:15]
	v_mfma_f32_16x16x32_bf16 v[8:11], v[182:185], v[234:237], v[8:11]
	v_mfma_f32_16x16x32_bf16 v[4:7], v[170:173], v[242:245], v[4:7]
	v_mfma_f32_16x16x32_bf16 v[0:3], v[182:185], v[242:245], v[0:3]
	s_setprio 0
	s_barrier
	s_add_i32 s26, 0, 0x1c000
	v_add_u32_e32 v162, s74, v175
	v_add_u32_e32 v177, s26, v175
	ds_read_b128 v[128:131], v162
	ds_read_b128 v[142:145], v162 offset:1024
	ds_read_b128 v[158:161], v162 offset:2048
	ds_read_b128 v[162:165], v162 offset:3072
	ds_read_b128 v[166:169], v177
	ds_read_b128 v[170:173], v177 offset:1024
	ds_read_b128 v[178:181], v177 offset:2048
	ds_read_b128 v[182:185], v177 offset:3072
	s_add_u32 s20, s30, s88
	s_addc_u32 s21, s31, 0
	s_mov_b32 m0, s82
	ds_read_b128 v[186:189], v176 offset:32768
	ds_read_b128 v[190:193], v176 offset:33792
	ds_read_b128 v[194:197], v176 offset:34816
	ds_read_b128 v[220:223], v176 offset:35840
	ds_read_b128 v[230:233], v176 offset:36864
	ds_read_b128 v[234:237], v176 offset:37888
	ds_read_b128 v[238:241], v176 offset:38912
	ds_read_b128 v[242:245], v176 offset:39936
	global_load_lds_dwordx4 v132, s[20:21]
	s_mov_b32 m0, s96
	s_nop 0
	global_load_lds_dwordx4 v134, s[20:21]
	s_waitcnt vmcnt(8)
	s_waitcnt lgkmcnt(0)
	s_barrier
	s_setprio 1
	s_waitcnt lgkmcnt(0)
	v_mfma_f32_16x16x32_bf16 v[124:127], v[128:131], v[186:189], v[124:127]
	v_mfma_f32_16x16x32_bf16 v[120:123], v[158:161], v[186:189], v[120:123]
	v_mfma_f32_16x16x32_bf16 v[116:119], v[128:131], v[194:197], v[116:119]
	v_mfma_f32_16x16x32_bf16 v[112:115], v[158:161], v[194:197], v[112:115]
	v_mfma_f32_16x16x32_bf16 v[108:111], v[128:131], v[230:233], v[108:111]
	v_mfma_f32_16x16x32_bf16 v[104:107], v[158:161], v[230:233], v[104:107]
	v_mfma_f32_16x16x32_bf16 v[100:103], v[128:131], v[238:241], v[100:103]
	v_mfma_f32_16x16x32_bf16 v[96:99], v[158:161], v[238:241], v[96:99]
	v_mfma_f32_16x16x32_bf16 v[124:127], v[142:145], v[190:193], v[124:127]
	v_mfma_f32_16x16x32_bf16 v[120:123], v[162:165], v[190:193], v[120:123]
	v_mfma_f32_16x16x32_bf16 v[116:119], v[142:145], v[220:223], v[116:119]
	v_mfma_f32_16x16x32_bf16 v[112:115], v[162:165], v[220:223], v[112:115]
	v_mfma_f32_16x16x32_bf16 v[108:111], v[142:145], v[234:237], v[108:111]
	v_mfma_f32_16x16x32_bf16 v[104:107], v[162:165], v[234:237], v[104:107]
	v_mfma_f32_16x16x32_bf16 v[100:103], v[142:145], v[242:245], v[100:103]
	v_mfma_f32_16x16x32_bf16 v[96:99], v[162:165], v[242:245], v[96:99]
	s_setprio 0
	s_setprio 1
	v_mfma_f32_16x16x32_bf16 v[60:63], v[166:169], v[186:189], v[60:63]
	v_mfma_f32_16x16x32_bf16 v[56:59], v[178:181], v[186:189], v[56:59]
	v_mfma_f32_16x16x32_bf16 v[52:55], v[166:169], v[194:197], v[52:55]
	v_mfma_f32_16x16x32_bf16 v[48:51], v[178:181], v[194:197], v[48:51]
	v_mfma_f32_16x16x32_bf16 v[44:47], v[166:169], v[230:233], v[44:47]
	v_mfma_f32_16x16x32_bf16 v[40:43], v[178:181], v[230:233], v[40:43]
	v_mfma_f32_16x16x32_bf16 v[36:39], v[166:169], v[238:241], v[36:39]
	v_mfma_f32_16x16x32_bf16 v[32:35], v[178:181], v[238:241], v[32:35]
	v_mfma_f32_16x16x32_bf16 v[60:63], v[170:173], v[190:193], v[60:63]
	v_mfma_f32_16x16x32_bf16 v[56:59], v[182:185], v[190:193], v[56:59]
	v_mfma_f32_16x16x32_bf16 v[52:55], v[170:173], v[220:223], v[52:55]
	v_mfma_f32_16x16x32_bf16 v[48:51], v[182:185], v[220:223], v[48:51]
	v_mfma_f32_16x16x32_bf16 v[44:47], v[170:173], v[234:237], v[44:47]
	v_mfma_f32_16x16x32_bf16 v[40:43], v[182:185], v[234:237], v[40:43]
	v_mfma_f32_16x16x32_bf16 v[36:39], v[170:173], v[242:245], v[36:39]
	v_mfma_f32_16x16x32_bf16 v[32:35], v[182:185], v[242:245], v[32:35]
	s_setprio 0
	s_barrier
; #define PG8_STAGE(bufoff, gbase, voff) do { _Pragma("unroll") for (int _i = 0; _i < 2; ++_i) \
;         __builtin_amdgcn_global_load_lds((const unsigned*)((const char*)(gbase) + (voff)[_i]), (LAS unsigned*)(lds + (bufoff) + ldsw + _i * 8192), 16, 0, 0); } while (0)
; #define PG8_LDA(dst, b, h) do { _Pragma("unroll") for (int m = 0; m < 4; ++m) _Pragma("unroll") for (int k = 0; k < 2; ++k) dst[m][k] = *(const LAS bf16x8*)(lds + PG8_SA(b, h) + aoff + m * 2048 + k * 1024); } while (0)
; #define PG8_MMA(ai, bj, At, Bt) do { __builtin_amdgcn_s_setprio(1); _Pragma("unroll") for (int m = 0; m < 4; ++m) _Pragma("unroll") for (int n = 0; n < 2; ++n) _Pragma("unroll") for (int k = 0; k < 2; ++k) \
;         acc[ai][bj][m][n] = __builtin_amdgcn_mfma_f32_16x16x32_bf16(Bt[n][k], At[m][k], acc[ai][bj][m][n], 0, 0, 0); __builtin_amdgcn_s_setprio(0); } while (0)
; #define PG8_WAIT_V(n) asm volatile("s_waitcnt vmcnt(" #n ")" ::: "memory")
; #define PG8_WAIT_L(n) asm volatile("s_waitcnt lgkmcnt(" #n ")" ::: "memory")
; #define PG8_BAR __builtin_amdgcn_s_barrier()
; #define PG8_SCHED __builtin_amdgcn_sched_barrier(0)
; template <class Epi>
; DI void gemm_phase(LAS unsigned char* lds, const Gemm g, const StaticOrder S, const Epi E) {
;     ...
;             PG8_LDA(At, 1, 1); PG8_STAGE(PG8_SB(1, 0), b3, voffB); PG8_STAGE(PG8_SB(1, 1), b3 + hstepB, voffB); PG8_STAGE(PG8_SA(1, 0), a3, voffA);
;             PG8_WAIT_V(8); PG8_WAIT_L(0); PG8_BAR; PG8_MMA(1, 0, At, B0); PG8_MMA(1, 1, At, B1); PG8_BAR; PG8_SCHED;
;         }
	s_add_i32 s20, s74, s81
	s_mov_b32 m0, s20
	ds_read_b128 v[186:189], v176 offset:49152
	ds_read_b128 v[190:193], v176 offset:50176
	ds_read_b128 v[194:197], v176 offset:51200
	ds_read_b128 v[220:223], v176 offset:52224
	ds_read_b128 v[230:233], v176 offset:53248
	ds_read_b128 v[234:237], v176 offset:54272
	ds_read_b128 v[238:241], v176 offset:55296
	ds_read_b128 v[242:245], v176 offset:56320
	global_load_lds_dwordx4 v146, s[98:99]
	s_add_i32 m0, s20, 0x2000
	s_add_i32 s20, s26, s81
	global_load_lds_dwordx4 v136, s[98:99]
	s_mov_b32 m0, s20
	s_nop 0
	global_load_lds_dwordx4 v146, s[100:101]
	s_add_i32 m0, s20, 0x2000
	s_nop 0
	global_load_lds_dwordx4 v136, s[100:101]
	s_mov_b32 m0, s86
	s_nop 0
	s_add_u32 s98, s30, 0x80
	s_addc_u32 s99, s31, 0
	global_load_lds_dwordx4 v132, s[98:99]
	s_mov_b32 m0, s87
	s_nop 0
	global_load_lds_dwordx4 v134, s[98:99]
	s_waitcnt vmcnt(8)
	s_waitcnt lgkmcnt(0)
	s_barrier
	s_setprio 1
	s_waitcnt lgkmcnt(0)
	v_mfma_f32_16x16x32_bf16 v[92:95], v[128:131], v[186:189], v[92:95]
	v_mfma_f32_16x16x32_bf16 v[88:91], v[158:161], v[186:189], v[88:91]
	v_mfma_f32_16x16x32_bf16 v[84:87], v[128:131], v[194:197], v[84:87]
	v_mfma_f32_16x16x32_bf16 v[80:83], v[158:161], v[194:197], v[80:83]
	v_mfma_f32_16x16x32_bf16 v[76:79], v[128:131], v[230:233], v[76:79]
	v_mfma_f32_16x16x32_bf16 v[72:75], v[158:161], v[230:233], v[72:75]
	v_mfma_f32_16x16x32_bf16 v[68:71], v[128:131], v[238:241], v[68:71]
	v_mfma_f32_16x16x32_bf16 v[64:67], v[158:161], v[238:241], v[64:67]
	v_mfma_f32_16x16x32_bf16 v[92:95], v[142:145], v[190:193], v[92:95]
	v_mfma_f32_16x16x32_bf16 v[88:91], v[162:165], v[190:193], v[88:91]
	v_mfma_f32_16x16x32_bf16 v[84:87], v[142:145], v[220:223], v[84:87]
	v_mfma_f32_16x16x32_bf16 v[80:83], v[162:165], v[220:223], v[80:83]
	v_mfma_f32_16x16x32_bf16 v[76:79], v[142:145], v[234:237], v[76:79]
	v_mfma_f32_16x16x32_bf16 v[72:75], v[162:165], v[234:237], v[72:75]
	v_mfma_f32_16x16x32_bf16 v[68:71], v[142:145], v[242:245], v[68:71]
	v_mfma_f32_16x16x32_bf16 v[64:67], v[162:165], v[242:245], v[64:67]
	s_setprio 0
	s_setprio 1
	v_mfma_f32_16x16x32_bf16 v[28:31], v[166:169], v[186:189], v[28:31]
	v_mfma_f32_16x16x32_bf16 v[24:27], v[178:181], v[186:189], v[24:27]
	v_mfma_f32_16x16x32_bf16 v[20:23], v[166:169], v[194:197], v[20:23]
	v_mfma_f32_16x16x32_bf16 v[16:19], v[178:181], v[194:197], v[16:19]
	v_mfma_f32_16x16x32_bf16 v[12:15], v[166:169], v[230:233], v[12:15]
	v_mfma_f32_16x16x32_bf16 v[8:11], v[178:181], v[230:233], v[8:11]
	v_mfma_f32_16x16x32_bf16 v[4:7], v[166:169], v[238:241], v[4:7]
	v_mfma_f32_16x16x32_bf16 v[0:3], v[178:181], v[238:241], v[0:3]
	v_mfma_f32_16x16x32_bf16 v[28:31], v[170:173], v[190:193], v[28:31]
	v_mfma_f32_16x16x32_bf16 v[24:27], v[182:185], v[190:193], v[24:27]
	v_mfma_f32_16x16x32_bf16 v[20:23], v[170:173], v[220:223], v[20:23]
	v_mfma_f32_16x16x32_bf16 v[16:19], v[182:185], v[220:223], v[16:19]
	v_mfma_f32_16x16x32_bf16 v[12:15], v[170:173], v[234:237], v[12:15]
	v_mfma_f32_16x16x32_bf16 v[8:11], v[182:185], v[234:237], v[8:11]
	v_mfma_f32_16x16x32_bf16 v[4:7], v[170:173], v[242:245], v[4:7]
	v_mfma_f32_16x16x32_bf16 v[0:3], v[182:185], v[242:245], v[0:3]
	s_setprio 0
	s_barrier
	s_add_u32 s42, s42, 0x100
	s_addc_u32 s43, s43, 0
	s_add_u32 s44, s44, 0x100
	s_addc_u32 s45, s45, 0
	s_cmp_ge_i32 vcc_lo, s2
	s_mov_b32 s30, vcc_lo
	s_cbranch_scc0 .LBB0_430
	s_and_b64 vcc, exec, s[60:61]
	s_cbranch_vccz .LBB0_433
	s_barrier
